# phase 0: nt (streaming) policy on the once-read f32 input loads (x rows, W_in tiles)
# speedup vs baseline: 1.0144x; 1.0049x over previous
.Lp0_nogain:
	global_load_dwordx4 v[36:39], v[2:3], off nt
	global_load_dwordx4 v[40:43], v[30:31], off nt
	global_load_dwordx4 v[44:47], v[32:33], off nt
	global_load_dwordx4 v[48:51], v[34:35], off nt
	s_waitcnt vmcnt(3)
	v_pk_mul_f32 v[2:3], v[36:37], v[52:53] op_sel_hi:[1,0]
	ds_write2_b32 v25, v2, v3 offset1:1
	v_pk_mul_f32 v[2:3], v[38:39], v[52:53] op_sel_hi:[1,0]
	ds_write2_b32 v25, v2, v3 offset0:2 offset1:3
	s_waitcnt vmcnt(2)
	v_pk_mul_f32 v[2:3], v[40:41], v[54:55] op_sel_hi:[1,0]
	ds_write2_b32 v26, v2, v3 offset1:1
	v_pk_mul_f32 v[2:3], v[42:43], v[54:55] op_sel_hi:[1,0]
	ds_write2_b32 v26, v2, v3 offset0:2 offset1:3
	s_waitcnt vmcnt(1)
	v_pk_mul_f32 v[2:3], v[44:45], v[56:57] op_sel_hi:[1,0]
	ds_write2_b32 v27, v2, v3 offset1:1
	v_pk_mul_f32 v[2:3], v[46:47], v[56:57] op_sel_hi:[1,0]
	ds_write2_b32 v27, v2, v3 offset0:2 offset1:3
	s_branch .LBB0_17

.LBB0_29:
	v_add_u32_e32 v2, 0xffffc000, v50
	v_cmp_gt_i32_e32 vcc, s29, v50
	v_add_u32_e32 v66, s27, v50
	v_add_u32_e32 v64, s28, v50
	v_cndmask_b32_e32 v3, 0, v51, vcc
	v_cndmask_b32_e32 v2, v2, v50, vcc
	v_cndmask_b32_e32 v5, v78, v79, vcc
	v_cndmask_b32_e32 v4, v80, v81, vcc
	v_lshlrev_b64 v[2:3], 12, v[2:3]
	v_lshl_add_u64 v[2:3], v[4:5], 0, v[2:3]
	v_lshl_add_u64 v[2:3], v[2:3], 0, v[52:53]
	global_load_dwordx4 v[82:85], v[2:3], off nt
	global_load_dwordx4 v[86:89], v[2:3], off offset:1024 nt
	global_load_dwordx4 v[90:93], v[2:3], off offset:2048 nt
	global_load_dwordx4 v[94:97], v[2:3], off offset:3072 nt
	v_add_u32_e32 v4, s14, v50
	v_lshl_add_u64 v[2:3], s[14:15], 0, v[50:51]
	v_min_i32_e32 v6, 0x407f, v4
	v_min_i32_e32 v8, 0x407f, v66
	v_lshl_add_u64 v[4:5], s[14:15], 0, v[2:3]
	v_add_u32_e32 v7, 0xffffc000, v6
	v_ashrrev_i32_e32 v3, 31, v6
	v_cmp_gt_i32_e32 vcc, s29, v2
	v_min_i32_e32 v10, 0x407f, v64
	v_add_u32_e32 v9, 0xffffc000, v8
	v_ashrrev_i32_e32 v11, 31, v8
	v_lshl_add_u64 v[68:69], s[14:15], 0, v[4:5]
	v_cndmask_b32_e32 v3, 0, v3, vcc
	v_cndmask_b32_e32 v2, v7, v6, vcc
	v_cndmask_b32_e32 v7, v78, v79, vcc
	v_cndmask_b32_e32 v6, v80, v81, vcc
	v_cmp_gt_i32_e32 vcc, s29, v4
	v_add_u32_e32 v12, 0xffffc000, v10
	v_ashrrev_i32_e32 v13, 31, v10
	v_cndmask_b32_e32 v5, 0, v11, vcc
	v_cndmask_b32_e32 v4, v9, v8, vcc
	v_cndmask_b32_e32 v9, v78, v79, vcc
	v_cndmask_b32_e32 v8, v80, v81, vcc
	v_cmp_gt_i32_e32 vcc, s29, v68
	v_lshlrev_b64 v[2:3], 12, v[2:3]
	v_lshlrev_b64 v[4:5], 12, v[4:5]
	v_cndmask_b32_e32 v11, 0, v13, vcc
	v_cndmask_b32_e32 v10, v12, v10, vcc
	v_cndmask_b32_e32 v13, v78, v79, vcc
	v_cndmask_b32_e32 v12, v80, v81, vcc
	v_lshl_add_u64 v[2:3], v[6:7], 0, v[2:3]
	v_lshlrev_b64 v[6:7], 12, v[10:11]
	v_lshl_add_u64 v[4:5], v[8:9], 0, v[4:5]
	v_lshl_add_u64 v[98:99], v[2:3], 0, v[52:53]
	v_lshl_add_u64 v[2:3], v[12:13], 0, v[6:7]
	v_lshl_add_u64 v[100:101], v[4:5], 0, v[52:53]
	global_load_dwordx4 v[46:49], v[98:99], off nt
	global_load_dwordx4 v[42:45], v[98:99], off offset:1024 nt
	v_lshl_add_u64 v[102:103], v[2:3], 0, v[52:53]
	global_load_dwordx4 v[38:41], v[98:99], off offset:2048 nt
	global_load_dwordx4 v[34:37], v[98:99], off offset:3072 nt
	global_load_dwordx4 v[30:33], v[100:101], off nt
	global_load_dwordx4 v[26:29], v[100:101], off offset:1024 nt
	global_load_dwordx4 v[22:25], v[100:101], off offset:2048 nt
	s_waitcnt lgkmcnt(0)
	global_load_dwordx4 v[18:21], v[100:101], off offset:3072 nt
	global_load_dwordx4 v[14:17], v[102:103], off nt
	global_load_dwordx4 v[10:13], v[102:103], off offset:1024 nt
	global_load_dwordx4 v[6:9], v[102:103], off offset:2048 nt
	global_load_dwordx4 v[2:5], v[102:103], off offset:3072 nt
	s_waitcnt vmcnt(15)
	v_pk_mul_f32 v[98:99], v[82:83], v[82:83]
	s_waitcnt vmcnt(14)
	v_pk_mul_f32 v[102:103], v[86:87], v[86:87]
	v_pk_mul_f32 v[100:101], v[84:85], v[84:85]
	v_pk_mul_f32 v[104:105], v[88:89], v[88:89]
	s_waitcnt vmcnt(13)
	v_pk_mul_f32 v[106:107], v[90:91], v[90:91]
	v_add_f32_e32 v65, v102, v103
	v_add_f32_e32 v67, v98, v99
	v_pk_mul_f32 v[108:109], v[92:93], v[92:93]
	s_waitcnt vmcnt(12)
	v_pk_mul_f32 v[110:111], v[94:95], v[94:95]
	v_add_f32_e32 v98, v106, v107
	v_add_f32_e32 v65, v65, v104
	v_add_f32_e32 v67, v67, v100
	v_pk_mul_f32 v[112:113], v[96:97], v[96:97]
	v_add_f32_e32 v99, v110, v111
	v_add_f32_e32 v98, v98, v108
	v_add_f32_e32 v65, v65, v105
	v_add_f32_e32 v67, v67, v101
	v_add_f32_e32 v99, v99, v112
	v_add_f32_e32 v98, v98, v109
	v_add_f32_e32 v65, v67, v65
	v_add_f32_e32 v99, v99, v113
	v_add_f32_e32 v65, v65, v98
	v_add_f32_e32 v65, v65, v99
	ds_bpermute_b32 v67, v72, v65
	v_lshl_add_u64 v[98:99], s[8:9], 0, v[62:63]
	v_add_co_u32_e32 v98, vcc, s7, v98
	v_cvt_pk_bf16_f32 v82, v82, v83
	s_waitcnt lgkmcnt(0)
	v_add_f32_e32 v65, v65, v67
	ds_bpermute_b32 v67, v73, v65
	v_addc_co_u32_e32 v99, vcc, 0, v99, vcc
	v_cvt_pk_bf16_f32 v83, v84, v85
	global_store_dwordx2 v[98:99], v[82:83], off
	s_waitcnt lgkmcnt(0)
	v_add_f32_e32 v65, v65, v67
	ds_bpermute_b32 v67, v74, v65
	v_cvt_pk_bf16_f32 v82, v86, v87
	v_cvt_pk_bf16_f32 v83, v88, v89
	global_store_dwordx2 v[98:99], v[82:83], off offset:512
	v_cvt_pk_bf16_f32 v82, v90, v91
	s_waitcnt lgkmcnt(0)
	v_add_f32_e32 v65, v65, v67
	ds_bpermute_b32 v67, v75, v65
	v_cvt_pk_bf16_f32 v83, v92, v93
	global_store_dwordx2 v[98:99], v[82:83], off offset:1024
	v_cvt_pk_bf16_f32 v82, v94, v95
	v_cvt_pk_bf16_f32 v83, v96, v97
	s_waitcnt lgkmcnt(0)
	v_add_f32_e32 v65, v65, v67
	ds_bpermute_b32 v67, v76, v65
	global_store_dwordx2 v[98:99], v[82:83], off offset:1536
	s_waitcnt lgkmcnt(0)
	v_add_f32_e32 v65, v65, v67
	ds_bpermute_b32 v67, v77, v65
	s_and_saveexec_b64 s[4:5], s[2:3]
	s_cbranch_execz .LBB0_31
	s_waitcnt lgkmcnt(0)
	v_add_f32_e32 v65, v65, v67
	v_lshl_add_u64 v[82:83], s[8:9], 0, v[60:61]
	global_store_dword v[82:83], v65, off
